# as v92 plus s_waitcnt vmcnt(0) before each seam's closing barrier (every wave drains its touch loads before the next phase's code runs)
# speedup vs baseline: 1.0278x; 1.0019x over previous
.LBB0_74:
	s_or_b64 exec, exec, s[6:7]
	s_waitcnt lgkmcnt(0)
	s_waitcnt vmcnt(0)
	s_barrier

.LBB0_161:
	s_or_b64 exec, exec, s[0:1]
	s_waitcnt lgkmcnt(0)
	s_waitcnt vmcnt(0)
	s_barrier

.LBB0_755:
	s_or_b64 exec, exec, s[4:5]
	s_waitcnt lgkmcnt(0)
	s_waitcnt vmcnt(0)
	s_barrier
